# block_cumsum (3 sites in P2): first element load no longer waited separately (one memory round trip instead of two)
# speedup vs baseline: 1.0020x; 1.0020x over previous
.LBB0_966:
	v_cndmask_b32_e64 v0, 0, 1, s[58:59]
	s_cmp_lg_u32 s2, s57
	v_cmp_ne_u32_e64 s[4:5], 1, v0
	s_mov_b64 s[2:3], -1
	s_cbranch_scc0 .LBB0_1102
	s_mov_b64 s[2:3], s[0:1]
	s_mov_b64 s[6:7], s[0:1]
	s_mov_b64 s[8:9], s[0:1]
	s_and_b64 vcc, exec, s[4:5]
	s_cbranch_vccnz .LBB0_1101
	s_mov_b64 s[10:11], s[0:1]
	s_load_dwordx2 s[10:11], s[10:11], 0x20
	v_readlane_b32 s12, v255, 11
	v_readlane_b32 s13, v255, 12
	v_mov_b32_e32 v10, v219
	s_waitcnt lgkmcnt(0)
	s_add_u32 s10, s10, s12
	s_addc_u32 s11, s11, s13
	v_readlane_b32 s12, v254, 45
	s_add_u32 s20, s10, s12
	s_movk_i32 s10, 0x200
	s_addc_u32 s21, s11, 0
	v_lshlrev_b32_e32 v0, 3, v10
	v_cmp_gt_i32_e32 vcc, s10, v10
	v_mov_b32_e32 v4, 0
	v_mov_b32_e32 v1, 0
	s_and_saveexec_b64 s[10:11], vcc
	s_cbranch_execz .LBB0_970
	v_ashrrev_i32_e32 v1, 31, v0
	v_lshlrev_b64 v[2:3], 5, v[0:1]
	v_lshl_add_u64 v[2:3], s[20:21], 0, v[2:3]
	global_load_dword v1, v[2:3], off
.LBB0_970:
	s_or_b64 exec, exec, s[10:11]
	s_load_dwordx2 s[24:25], s[2:3], 0xb0
	s_load_dwordx2 s[22:23], s[6:7], 0xa8
	s_nop 0
	s_load_dwordx2 s[2:3], s[8:9], 0xb0
	v_or_b32_e32 v2, 1, v0
	s_movk_i32 s30, 0x1000
	v_cmp_gt_i32_e64 s[6:7], s30, v2
	s_and_saveexec_b64 s[8:9], s[6:7]
	s_cbranch_execz .LBB0_972
	v_ashrrev_i32_e32 v3, 31, v2
	v_lshlrev_b64 v[2:3], 5, v[2:3]
	v_lshl_add_u64 v[2:3], s[20:21], 0, v[2:3]
	global_load_dword v4, v[2:3], off

.LBB0_984:
	s_or_b64 exec, exec, s[26:27]
	s_waitcnt vmcnt(0)
	v_add_f32_e32 v1, 0, v1
	v_add_f32_e32 v8, v1, v4
	v_add_f32_e32 v7, v8, v6
	v_add_f32_e32 v6, v7, v5
	v_add_f32_e32 v5, v6, v11
	v_add_f32_e32 v4, v5, v9
	v_add_f32_e32 v3, v4, v13
	v_add_f32_e32 v2, v3, v12
	v_and_b32_e32 v11, 63, v10
	v_ashrrev_i32_e32 v9, 6, v10
	v_add_f32_dpp v12, v2, v2 row_shr:1 row_mask:0xf bank_mask:0xf bound_ctrl:1
	v_and_b32_e32 v10, 48, v10
	s_nop 0
	v_add_f32_dpp v12, v12, v12 row_shr:2 row_mask:0xf bank_mask:0xf bound_ctrl:1
	s_nop 1
	v_add_f32_dpp v12, v12, v12 row_shr:4 row_mask:0xf bank_mask:0xf bound_ctrl:1
	s_nop 1
	v_add_f32_dpp v12, v12, v12 row_shr:8 row_mask:0xf bank_mask:0xf bound_ctrl:1
	s_nop 0
	v_readlane_b32 s20, v12, 15
	v_readlane_b32 s26, v12, 31
	v_readlane_b32 s27, v12, 47
	v_mov_b32_e32 v13, s20
	v_cmp_lt_u32_e64 s[20:21], 15, v11
	s_nop 1
	v_cndmask_b32_e64 v13, 0, v13, s[20:21]
	v_add_f32_e32 v12, v12, v13
	v_mov_b32_e32 v13, s26
	v_cmp_lt_u32_e64 s[20:21], 31, v11
	s_nop 1
	v_cndmask_b32_e64 v13, 0, v13, s[20:21]
	v_add_f32_e32 v12, v12, v13
	v_mov_b32_e32 v13, s27
	v_cmp_eq_u32_e64 s[20:21], 48, v10
	s_nop 1
	v_cndmask_b32_e64 v10, 0, v13, s[20:21]
	v_add_f32_e32 v10, v12, v10
	v_cmp_eq_u32_e64 s[20:21], 63, v11
	s_and_saveexec_b64 s[26:27], s[20:21]
	v_lshl_add_u32 v11, v9, 2, 0
	v_add_u32_e32 v11, 0x19400, v11
	ds_write_b32 v11, v10
	s_or_b64 exec, exec, s[26:27]
	s_add_i32 s26, 0, 0x19400
	v_sub_f32_e32 v14, v10, v2
	v_mov_b32_e32 v10, s26
	s_waitcnt lgkmcnt(0)
	s_barrier
	ds_read_b128 v[10:13], v10
	v_cmp_lt_i32_e64 s[20:21], 0, v9
	v_lshl_add_u32 v0, v0, 2, 0
	s_waitcnt lgkmcnt(0)
	v_add_f32_e32 v15, v14, v10
	v_cndmask_b32_e64 v14, v14, v15, s[20:21]
	v_cmp_lt_i32_e64 s[20:21], 1, v9
	v_add_f32_e32 v15, v11, v14
	v_add_f32_e32 v10, 0, v10
	v_cndmask_b32_e64 v14, v14, v15, s[20:21]
	v_add_f32_e32 v10, v10, v11
	v_cmp_lt_i32_e64 s[20:21], 2, v9
	v_add_f32_e32 v11, v12, v14
	v_add_f32_e32 v10, v10, v12
	v_cndmask_b32_e64 v11, v14, v11, s[20:21]
	v_cmp_lt_i32_e64 s[20:21], 3, v9
	v_add_f32_e32 v12, v13, v11
	v_add_f32_e32 v15, v10, v13
	v_cndmask_b32_e64 v14, v11, v12, s[20:21]
	v_readlane_b32 s20, v253, 11
	s_nop 1
	v_mov_b32_e32 v10, s20
	ds_read_b128 v[10:13], v10
	v_cmp_lt_i32_e64 s[20:21], 4, v9
	s_waitcnt lgkmcnt(0)
	v_add_f32_e32 v16, v10, v14
	v_cndmask_b32_e64 v14, v14, v16, s[20:21]
	v_add_f32_e32 v10, v15, v10
	v_cmp_lt_i32_e64 s[20:21], 5, v9
	v_add_f32_e32 v15, v11, v14
	v_add_f32_e32 v10, v10, v11
	v_cndmask_b32_e64 v14, v14, v15, s[20:21]
	v_cmp_lt_i32_e64 s[20:21], 6, v9
	v_add_f32_e32 v11, v12, v14
	v_add_f32_e32 v10, v10, v12
	v_cndmask_b32_e64 v11, v14, v11, s[20:21]
	v_cmp_lt_i32_e64 s[20:21], 7, v9
	v_add_f32_e32 v9, v13, v11
	v_add_f32_e32 v10, v10, v13
	v_cndmask_b32_e64 v9, v11, v9, s[20:21]
	s_and_saveexec_b64 s[20:21], vcc
	s_cbranch_execnz .LBB0_1015
	s_or_b64 exec, exec, s[20:21]
	s_and_saveexec_b64 s[20:21], s[6:7]
	s_cbranch_execnz .LBB0_1016

.LBB0_1027:
	s_or_b64 exec, exec, s[6:7]
	s_waitcnt lgkmcnt(7)
	v_pk_fma_f32 v[28:29], v[28:29], v[42:43], 0 op_sel_hi:[1,0,0]
	v_pk_fma_f32 v[30:31], v[30:31], v[42:43], 0 op_sel_hi:[1,0,0]
	s_waitcnt lgkmcnt(6)
	v_pk_fma_f32 v[12:13], v[12:13], v[46:47], v[28:29] op_sel_hi:[1,0,1]
	v_pk_fma_f32 v[14:15], v[14:15], v[46:47], v[30:31] op_sel_hi:[1,0,1]
	s_waitcnt lgkmcnt(5)
	v_pk_fma_f32 v[12:13], v[16:17], v[44:45], v[12:13] op_sel_hi:[1,0,1]
	v_lshlrev_b32_e32 v33, 2, v35
	s_waitcnt lgkmcnt(4)
	v_pk_fma_f32 v[0:1], v[0:1], v[38:39], v[12:13] op_sel_hi:[1,0,1]
	v_pk_fma_f32 v[14:15], v[18:19], v[44:45], v[14:15] op_sel_hi:[1,0,1]
	s_waitcnt lgkmcnt(3)
	v_pk_fma_f32 v[0:1], v[20:21], v[36:37], v[0:1] op_sel_hi:[1,0,1]
	v_pk_fma_f32 v[2:3], v[2:3], v[38:39], v[14:15] op_sel_hi:[1,0,1]
	s_waitcnt lgkmcnt(2)
	v_pk_fma_f32 v[0:1], v[34:35], v[4:5], v[0:1] op_sel_hi:[0,1,1]
	v_lshlrev_b32_e32 v4, 7, v32
	v_ashrrev_i32_e32 v5, 31, v4
	v_lshl_add_u64 v[4:5], v[4:5], 2, s[10:11]
	v_lshlrev_b32_e32 v96, 2, v33
	v_pk_fma_f32 v[2:3], v[22:23], v[36:37], v[2:3] op_sel_hi:[1,0,1]
	v_lshl_add_u64 v[4:5], v[4:5], 0, v[96:97]
	s_mov_b64 s[6:7], 0x208080
	v_pk_fma_f32 v[2:3], v[34:35], v[6:7], v[2:3] op_sel_hi:[0,1,1]
	v_lshl_add_u64 v[6:7], v[4:5], 0, s[6:7]
	s_mov_b32 s6, 0x208000
	s_waitcnt lgkmcnt(1)
	v_pk_fma_f32 v[0:1], v[40:41], v[24:25], v[0:1] op_sel_hi:[0,1,1]
	v_add_co_u32_e32 v4, vcc, s6, v4
	v_pk_fma_f32 v[2:3], v[40:41], v[26:27], v[2:3] op_sel_hi:[0,1,1]
	s_waitcnt lgkmcnt(0)
	v_pk_fma_f32 v[0:1], v[48:49], v[8:9], v[0:1] op_sel_hi:[0,1,1]
	v_addc_co_u32_e32 v5, vcc, 0, v5, vcc
	v_mov_b32_e32 v18, v219
	v_pk_fma_f32 v[2:3], v[48:49], v[10:11], v[2:3] op_sel_hi:[0,1,1]
	global_store_dword v[4:5], v0, off offset:128 sc1
	global_store_dword v[6:7], v1, off offset:4 sc1
	global_store_dword v[6:7], v2, off offset:8 sc1
	global_store_dword v[6:7], v3, off offset:12 sc1
	s_barrier
	v_readlane_b32 s6, v254, 48
	s_add_u32 s8, s14, s6
	s_movk_i32 s6, 0x1e3
	v_lshl_add_u32 v0, v18, 4, v18
	s_addc_u32 s9, s15, 0
	v_cmp_gt_i32_e32 vcc, s6, v18
	v_mov_b32_e32 v3, 0
	v_ashrrev_i32_e32 v1, 31, v0
	v_mov_b32_e32 v2, 0
	s_and_saveexec_b64 s[6:7], vcc
	s_cbranch_execz .LBB0_1029
	v_lshl_add_u64 v[4:5], v[0:1], 2, s[8:9]
	global_load_dword v2, v[4:5], off
.LBB0_1029:
	s_or_b64 exec, exec, s[6:7]
	s_and_saveexec_b64 s[6:7], vcc
	s_cbranch_execz .LBB0_1031
	v_lshl_add_u64 v[4:5], v[0:1], 2, s[8:9]
	global_load_dword v3, v[4:5], off offset:4

.LBB0_1059:
	s_or_b64 exec, exec, s[12:13]
	s_waitcnt vmcnt(0)
	v_add_f32_e32 v2, 0, v2
	v_add_f32_e32 v3, v2, v3
	v_add_f32_e32 v16, v3, v5
	v_add_f32_e32 v17, v16, v4
	v_add_f32_e32 v14, v17, v7
	v_add_f32_e32 v15, v14, v6
	v_add_f32_e32 v12, v15, v9
	v_add_f32_e32 v13, v12, v8
	v_add_f32_e32 v10, v13, v10
	v_add_f32_e32 v11, v10, v11
	v_add_f32_e32 v8, v11, v20
	v_add_f32_e32 v9, v8, v19
	v_add_f32_e32 v6, v9, v22
	v_add_f32_e32 v7, v6, v21
	v_add_f32_e32 v4, v7, v24
	v_add_f32_e32 v5, v4, v23
	v_add_f32_e32 v1, v5, v25
	v_and_b32_e32 v20, 63, v18
	v_ashrrev_i32_e32 v19, 6, v18
	v_add_f32_dpp v21, v1, v1 row_shr:1 row_mask:0xf bank_mask:0xf bound_ctrl:1
	v_and_b32_e32 v18, 48, v18
	s_nop 0
	v_add_f32_dpp v21, v21, v21 row_shr:2 row_mask:0xf bank_mask:0xf bound_ctrl:1
	s_nop 1
	v_add_f32_dpp v21, v21, v21 row_shr:4 row_mask:0xf bank_mask:0xf bound_ctrl:1
	s_nop 1
	v_add_f32_dpp v21, v21, v21 row_shr:8 row_mask:0xf bank_mask:0xf bound_ctrl:1
	s_nop 0
	v_readlane_b32 s8, v21, 15
	v_readlane_b32 s12, v21, 31
	v_readlane_b32 s13, v21, 47
	v_mov_b32_e32 v22, s8
	v_cmp_lt_u32_e64 s[8:9], 15, v20
	s_nop 1
	v_cndmask_b32_e64 v22, 0, v22, s[8:9]
	v_add_f32_e32 v21, v21, v22
	v_mov_b32_e32 v22, s12
	v_cmp_lt_u32_e64 s[8:9], 31, v20
	s_nop 1
	v_cndmask_b32_e64 v22, 0, v22, s[8:9]
	v_add_f32_e32 v21, v21, v22
	v_mov_b32_e32 v22, s13
	v_cmp_eq_u32_e64 s[8:9], 48, v18
	s_nop 1
	v_cndmask_b32_e64 v18, 0, v22, s[8:9]
	v_add_f32_e32 v18, v21, v18
	v_cmp_eq_u32_e64 s[8:9], 63, v20
	s_and_saveexec_b64 s[12:13], s[8:9]
	v_lshl_add_u32 v20, v19, 2, 0
	v_add_u32_e32 v20, 0x19400, v20
	ds_write_b32 v20, v18
	s_or_b64 exec, exec, s[12:13]
	v_sub_f32_e32 v18, v18, v1
	v_cmp_lt_i32_e64 s[8:9], 0, v19
	s_waitcnt lgkmcnt(0)
	s_barrier
	s_and_saveexec_b64 s[12:13], s[8:9]
	s_cbranch_execnz .LBB0_1080
	s_or_b64 exec, exec, s[12:13]
	v_cmp_lt_i32_e64 s[8:9], 1, v19
	s_and_saveexec_b64 s[12:13], s[8:9]
	s_cbranch_execnz .LBB0_1081

.LBB0_1102:
	s_andn2_b64 vcc, exec, s[2:3]
	s_cbranch_vccnz .LBB0_965
	s_mov_b64 s[2:3], s[0:1]
	s_mov_b64 s[6:7], s[0:1]
	s_mov_b64 s[14:15], s[0:1]
	s_mov_b64 s[8:9], s[0:1]
	s_mov_b64 s[10:11], s[0:1]
	s_mov_b64 s[12:13], s[0:1]
	s_and_b64 vcc, exec, s[4:5]
	s_cbranch_vccnz .LBB0_964
	s_load_dwordx2 s[4:5], s[14:15], 0xb0
	v_readlane_b32 s14, v254, 53
	v_mov_b32_e32 v21, v219
	v_mov_b32_e32 v18, 0
	s_waitcnt lgkmcnt(0)
	s_add_u32 s4, s4, s14
	s_addc_u32 s5, s5, 0
	s_add_u32 s36, s4, 0x32700000
	v_lshlrev_b32_e32 v0, 4, v21
	s_addc_u32 s37, s5, 0
	v_cmp_gt_i32_e32 vcc, s92, v0
	v_ashrrev_i32_e32 v1, 31, v0
	v_mov_b32_e32 v2, 0
	s_and_saveexec_b64 s[4:5], vcc
	s_cbranch_execz .LBB0_1106
	v_lshl_add_u64 v[2:3], v[0:1], 2, s[36:37]
	global_load_dword v2, v[2:3], off
.LBB0_1106:
	s_or_b64 exec, exec, s[4:5]
	s_load_dwordx2 s[42:43], s[2:3], 0xb0
	s_nop 0
	s_load_dwordx2 s[2:3], s[6:7], 0xb0
	s_load_dwordx2 s[74:75], s[8:9], 0xb0
	s_load_dwordx2 s[76:77], s[10:11], 0xb0
	s_load_dwordx2 s[38:39], s[12:13], 0xb0
	v_or_b32_e32 v3, 1, v0
	v_cmp_gt_i32_e64 s[4:5], s92, v3
	s_and_saveexec_b64 s[6:7], s[4:5]
	s_cbranch_execz .LBB0_1108
	v_lshl_add_u64 v[4:5], v[0:1], 2, s[36:37]
	global_load_dword v18, v[4:5], off offset:4

.LBB0_1136:
	s_or_b64 exec, exec, s[44:45]
	s_waitcnt vmcnt(0)
	v_add_f32_e32 v2, 0, v2
	v_add_f32_e32 v32, v2, v18
	v_add_f32_e32 v31, v32, v20
	v_add_f32_e32 v30, v31, v19
	v_add_f32_e32 v29, v30, v23
	v_add_f32_e32 v28, v29, v22
	v_add_f32_e32 v27, v28, v25
	v_add_f32_e32 v26, v27, v24
	v_add_f32_e32 v25, v26, v34
	v_add_f32_e32 v24, v25, v33
	v_add_f32_e32 v23, v24, v36
	v_add_f32_e32 v22, v23, v35
	v_add_f32_e32 v20, v22, v38
	v_add_f32_e32 v19, v20, v37
	v_add_f32_e32 v18, v19, v40
	v_add_f32_e32 v1, v18, v39
	v_and_b32_e32 v34, 63, v21
	v_ashrrev_i32_e32 v33, 6, v21
	v_add_f32_dpp v35, v1, v1 row_shr:1 row_mask:0xf bank_mask:0xf bound_ctrl:1
	v_and_b32_e32 v21, 48, v21
	s_nop 0
	v_add_f32_dpp v35, v35, v35 row_shr:2 row_mask:0xf bank_mask:0xf bound_ctrl:1
	s_nop 1
	v_add_f32_dpp v35, v35, v35 row_shr:4 row_mask:0xf bank_mask:0xf bound_ctrl:1
	s_nop 1
	v_add_f32_dpp v35, v35, v35 row_shr:8 row_mask:0xf bank_mask:0xf bound_ctrl:1
	s_nop 0
	v_readlane_b32 s36, v35, 15
	v_readlane_b32 s41, v35, 31
	v_readlane_b32 s44, v35, 47
	v_mov_b32_e32 v36, s36
	v_cmp_lt_u32_e64 s[36:37], 15, v34
	s_nop 1
	v_cndmask_b32_e64 v36, 0, v36, s[36:37]
	v_add_f32_e32 v35, v35, v36
	v_mov_b32_e32 v36, s41
	v_cmp_lt_u32_e64 s[36:37], 31, v34
	s_nop 1
	v_cndmask_b32_e64 v36, 0, v36, s[36:37]
	v_add_f32_e32 v35, v35, v36
	v_mov_b32_e32 v36, s44
	v_cmp_eq_u32_e64 s[36:37], 48, v21
	s_nop 1
	v_cndmask_b32_e64 v21, 0, v36, s[36:37]
	v_add_f32_e32 v21, v35, v21
	v_cmp_eq_u32_e64 s[36:37], 63, v34
	s_and_saveexec_b64 s[44:45], s[36:37]
	v_lshl_add_u32 v34, v33, 2, 0
	v_add_u32_e32 v34, 0x19400, v34
	ds_write_b32 v34, v21
	s_or_b64 exec, exec, s[44:45]
	v_sub_f32_e32 v21, v21, v1
	v_cmp_lt_i32_e64 s[36:37], 0, v33
	s_waitcnt lgkmcnt(0)
	s_barrier
	s_and_saveexec_b64 s[44:45], s[36:37]
	s_cbranch_execnz .LBB0_1181
	s_or_b64 exec, exec, s[44:45]
	v_cmp_lt_i32_e64 s[36:37], 1, v33
	s_and_saveexec_b64 s[44:45], s[36:37]
	s_cbranch_execnz .LBB0_1182
